# merge phase: odd workgroups run their split-tail task before the main tile (staggers the gate bursts); chain waits relaxed
# baseline (speedup 1.0000x reference)
; #define LAS __attribute__((address_space(3)))
; __global__ void __launch_bounds__(512, 2) mega_fwd(Params p) {
;     extern __shared__ __attribute__((aligned(16))) unsigned char lds_raw[];
;     Frame F;
;     F.lds = (LAS unsigned char*)lds_raw; F.MISC = (volatile LAS unsigned*)(F.lds + LDS_MISC);
;     F.wave = __builtin_amdgcn_readfirstlane((int)threadIdx.x >> 6);
;     F.G = gridDim.x; { const int bx = blockIdx.x; F.vcu = (F.G % 8 == 0) ? (bx % 8) * (F.G / 8) + bx / 8 : bx; }
;     if (threadIdx.x < 64) F.MISC[threadIdx.x] = 0u;
_Z8mega_fwd6Params:
	s_mov_b32 s101, s2
	s_mov_b32 s100, 0
	s_load_dword s3, s[0:1], 0xa0
	s_add_u32 s4, s0, 0xa0
	s_addc_u32 s5, s1, 0
	v_readfirstlane_b32 s34, v0
	v_writelane_b32 v243, s4, 0
	s_waitcnt lgkmcnt(0)
	s_mov_b32 s8, s3
	s_and_b32 s3, s3, 7
	s_cmp_lg_u32 s3, 0
	s_mov_b32 s60, s2
	s_mov_b32 s3, s2
	v_writelane_b32 v243, s5, 1
	s_cbranch_scc0 .LBB0_29
	s_load_dwordx2 s[64:65], s[0:1], 0x98
	v_cmp_gt_u32_e32 vcc, 64, v0
	s_and_saveexec_b64 s[4:5], vcc

; #define GAS __attribute__((address_space(1)))
; #define LAS __attribute__((address_space(3)))
;     __device__ __forceinline__ int tid_() const { return wave * 64 + lane_id(); }
; template <int PART>
; __device__ __forceinline__ void prefetch(Pre& P, const GAS unsigned char* ws, size_t row0, int nvalid, int seg, int colb  , int trow  , int sgcol  ) {
;     const GAS _Float16* LF = (const GAS _Float16*)(ws + WS_LOGF) + row0 * 1024; const GAS bf16* QC = (const GAS bf16*)(ws + WS_QC) + row0 * 1024; const GAS bf16* KC = (const GAS bf16*)(ws + WS_KC) + row0 * 1024; const GAS bf16* IC = (const GAS bf16*)(ws + WS_IC) + row0 * 1024;
;     if (PART & 2) { const GAS bf16* SGC = (const GAS bf16*)(ws + WS_SGC) + row0 * 1024; const unsigned so = (unsigned)((trow < nvalid ? trow : 0) * 1024 + sgcol);
; #pragma unroll
;       for (int g = 0; g < 4; ++g) P.sg[g] = *(const GAS v2u*)(SGC + so + 8 * g); }
;     if (nvalid == 64) {
; #pragma unroll
;         for (int i = 0; i < 8; ++i) { const unsigned o = (unsigned)((seg * 8 + i) * 1024 + colb);
;             if (PART & 1) P.lf[i] = *(const GAS unsigned*)(LF + o);
;             if (PART & 2) { P.q[i] = *(const GAS unsigned*)(QC + o); P.k[i] = *(const GAS unsigned*)(KC + o); P.v[i] = *(const GAS unsigned*)(IC + o); } }
;     } else {
; #pragma unroll
;         for (int i = 0; i < 8; ++i) { const int t = seg * 8 + i; const unsigned o = (unsigned)(t * 1024 + colb);
;             if (t < nvalid) { if (PART & 1) P.lf[i] = *(const GAS unsigned*)(LF + o); if (PART & 2) { P.q[i] = *(const GAS unsigned*)(QC + o); P.k[i] = *(const GAS unsigned*)(KC + o); P.v[i] = *(const GAS unsigned*)(IC + o); } }
;             else { if (PART & 1) P.lf[i] = 0u; if (PART & 2) { P.q[i] = 0u; P.k[i] = 0u; P.v[i] = 0u; } } }
;     }
; __device__ __forceinline__ void chain(Frame& F, int layer, bool sample, int b, int h) {
;     LAS unsigned char* lds = F.lds; int tid = F.tid_(); asm volatile("" : "+v"(tid));
;     const int lane = tid & 63, wave = F.wave, seg = wave; int kp = tid & 63, l31 = lane & 31, hh = lane >> 5;
;     const int L = sample ? DSEQ : LP, nchunks = (L + 63) / 64;
;     const size_t rowbase = sample ? (size_t)MPAD + (size_t)b * DSEQ : (size_t)b * LP;
;     const int colb = h * 128 + 2 * kp;
;     GAS bf16* YC = (GAS bf16*)(F.wsp() + WS_Y) + (size_t)2 * MTOT * 1024;
.LBB0_759:
	s_or_b64 exec, exec, s[58:59]
	v_and_b32_e32 v93, 63, v0
	v_mov_b32_e32 v0, s18
	ds_read_b64 v[0:1], v0
	s_lshl_b32 s20, s12, 7
	s_and_b64 s[16:17], s[56:57], exec
	s_cselect_b32 s13, 64, 0x810
	s_add_i32 s14, s13, 63
	s_lshr_b32 s14, s14, 6
	s_waitcnt lgkmcnt(0)
	v_readfirstlane_b32 s17, v0
	s_or_b32 s74, s20, s97
	s_lshl_b64 s[56:57], s[36:37], 10
	s_lshl_b64 s[58:59], s[36:37], 11
	v_readfirstlane_b32 s16, v1
	s_add_u32 s60, s17, s58
	s_addc_u32 s61, s16, s59
	s_add_u32 s16, s60, 0x18f80000
	s_addc_u32 s17, s61, 0
	s_add_u32 s52, s60, 0x14680000
	s_addc_u32 s53, s61, 0
	v_lshl_or_b32 v24, v93, 1, s20
	v_readlane_b32 s20, v242, 24
	s_add_u32 s62, s60, 0x16b00000
	s_addc_u32 s63, s61, 0
	v_or_b32_e32 v66, s20, v24
	v_or_b32_e32 v172, 0x1c00, v66
	s_add_u32 s64, s60, 0x24600000
	v_or_b32_e32 v74, 0x1400, v66
	v_mov_b32_e32 v75, v173
	v_or_b32_e32 v76, 0x1800, v66
	v_mov_b32_e32 v77, v173
	v_lshlrev_b64 v[0:1], 1, v[172:173]
	s_addc_u32 s65, s61, 0
	v_or_b32_e32 v70, 0xc00, v66
	v_mov_b32_e32 v71, v173
	v_or_b32_e32 v72, 0x1000, v66
	v_mov_b32_e32 v73, v173
	v_lshl_add_u64 v[2:3], s[16:17], 0, v[0:1]
	v_lshl_add_u64 v[4:5], s[52:53], 0, v[0:1]
	v_lshl_add_u64 v[6:7], s[62:63], 0, v[0:1]
	v_lshl_add_u64 v[0:1], s[64:65], 0, v[0:1]
	v_lshlrev_b64 v[80:81], 1, v[76:77]
	v_lshlrev_b64 v[82:83], 1, v[74:75]
	v_mov_b32_e32 v67, v173
	v_or_b32_e32 v68, 0x800, v66
	v_mov_b32_e32 v69, v173
	v_lshl_add_u64 v[8:9], s[16:17], 0, v[80:81]
	v_lshl_add_u64 v[10:11], s[52:53], 0, v[80:81]
	v_lshl_add_u64 v[12:13], s[62:63], 0, v[80:81]
	v_lshl_add_u64 v[14:15], s[64:65], 0, v[80:81]
	global_load_dword v143, v[2:3], off
	global_load_dword v142, v[4:5], off
	global_load_dword v141, v[6:7], off
	global_load_dword v129, v[0:1], off
	global_load_dword v140, v[8:9], off
	global_load_dword v139, v[10:11], off
	global_load_dword v138, v[12:13], off
	global_load_dword v118, v[14:15], off
	v_lshl_add_u64 v[0:1], s[16:17], 0, v[82:83]
	v_lshlrev_b64 v[84:85], 1, v[72:73]
	v_lshlrev_b64 v[86:87], 1, v[70:71]
	v_lshl_add_u64 v[2:3], s[52:53], 0, v[82:83]
	v_lshl_add_u64 v[4:5], s[62:63], 0, v[82:83]
	v_lshl_add_u64 v[6:7], s[64:65], 0, v[82:83]
	v_lshl_add_u64 v[8:9], s[16:17], 0, v[84:85]
	v_lshl_add_u64 v[10:11], s[52:53], 0, v[84:85]
	v_lshl_add_u64 v[12:13], s[62:63], 0, v[84:85]
	v_lshl_add_u64 v[14:15], s[64:65], 0, v[84:85]
	global_load_dword v136, v[0:1], off
	global_load_dword v137, v[2:3], off
	global_load_dword v135, v[4:5], off
	global_load_dword v117, v[6:7], off
	global_load_dword v132, v[8:9], off
	global_load_dword v133, v[10:11], off
	global_load_dword v134, v[12:13], off
	global_load_dword v101, v[14:15], off
	v_lshl_add_u64 v[0:1], s[16:17], 0, v[86:87]
	v_lshlrev_b64 v[88:89], 1, v[68:69]
	v_lshlrev_b64 v[90:91], 1, v[66:67]
	v_lshl_add_u64 v[2:3], s[52:53], 0, v[86:87]
	v_lshl_add_u64 v[4:5], s[62:63], 0, v[86:87]
	v_lshl_add_u64 v[6:7], s[64:65], 0, v[86:87]
	v_lshl_add_u64 v[8:9], s[16:17], 0, v[88:89]
	v_lshl_add_u64 v[10:11], s[52:53], 0, v[88:89]
	v_lshl_add_u64 v[12:13], s[62:63], 0, v[88:89]
	v_lshl_add_u64 v[14:15], s[64:65], 0, v[88:89]
	global_load_dword v130, v[0:1], off
	global_load_dword v131, v[2:3], off
	global_load_dword v128, v[4:5], off
	global_load_dword v103, v[6:7], off
	global_load_dword v127, v[8:9], off
	global_load_dword v126, v[10:11], off
	global_load_dword v125, v[12:13], off
	global_load_dword v99, v[14:15], off
	v_lshl_add_u64 v[0:1], s[16:17], 0, v[90:91]
	v_lshl_add_u64 v[2:3], s[52:53], 0, v[90:91]
	v_lshl_add_u64 v[4:5], s[62:63], 0, v[90:91]
	v_lshl_add_u64 v[6:7], s[64:65], 0, v[90:91]
	global_load_dword v123, v[0:1], off offset:2048
	global_load_dword v124, v[2:3], off offset:2048
	global_load_dword v119, v[4:5], off offset:2048
	global_load_dword v97, v[6:7], off offset:2048
	global_load_dword v95, v[6:7], off
	global_load_dword v120, v[4:5], off
	global_load_dword v121, v[2:3], off
	global_load_dword v122, v[0:1], off
	v_or_b32_e32 v0, s94, v32
	v_readlane_b32 s16, v242, 25
	v_lshlrev_b32_e32 v0, 10, v0
	v_readlane_b32 s17, v242, 26
	v_lshlrev_b32_e32 v1, 2, v33
	v_mov_b64_e32 v[78:79], v[172:173]
	v_cndmask_b32_e64 v0, 0, v0, s[16:17]
	v_or3_b32 v0, v0, v1, s74
	v_lshlrev_b32_e32 v172, 1, v0
	v_lshl_add_u64 v[0:1], s[60:61], 0, v[172:173]
	s_mov_b64 s[16:17], 0x1b400000
	v_lshl_add_u64 v[2:3], v[0:1], 0, s[16:17]
	s_mov_b32 s16, 0x1b400000
	v_add_co_u32_e32 v0, vcc, s16, v0
	v_readlane_b32 s16, v242, 27
	s_nop 0
	v_addc_co_u32_e32 v1, vcc, 0, v1, vcc
	global_load_dwordx2 v[16:17], v[2:3], off offset:48
	global_load_dwordx2 v[22:23], v[0:1], off
	global_load_dwordx2 v[18:19], v[2:3], off offset:32
	global_load_dwordx2 v[20:21], v[2:3], off offset:16
	v_or_b32_e32 v92, s16, v24
	v_readlane_b32 s16, v242, 28
	s_mov_b32 s62, 0
	s_nop 0
	v_or_b32_e32 v94, s16, v24
	v_readlane_b32 s16, v242, 29
	s_nop 1
	v_or_b32_e32 v96, s16, v24
	v_readlane_b32 s16, v242, 30
	s_nop 1
	v_or_b32_e32 v98, s16, v24
	v_readlane_b32 s16, v242, 31
	s_nop 1
	v_or_b32_e32 v100, s16, v24
	v_readlane_b32 s16, v242, 32
	s_nop 1
	v_or_b32_e32 v102, s16, v24
	v_readlane_b32 s16, v242, 33
	s_nop 1
	v_or_b32_e32 v172, s16, v24
	s_lshl_b32 s16, s12, 8
	s_add_u32 s16, s24, s16
	s_addc_u32 s15, s15, 0
	s_lshl_b32 s17, s97, 1
	s_add_u32 s16, s16, s17
	s_addc_u32 s15, s15, 0
	s_add_u32 s60, s16, 0x2d800000
	v_mov_b64_e32 v[104:105], v[172:173]
	s_addc_u32 s61, s15, 0
	s_waitcnt vmcnt(0)
	s_branch .LBB0_761
.Lch_skipL:
	s_waitcnt vmcnt(0)
	s_branch .LBB0_784
; #define LAS __attribute__((address_space(3)))
; __device__ __forceinline__ unsigned cvt_pk_bf16(float lo, float hi) { const f32x2 v = {lo, hi}; return __builtin_bit_cast(unsigned, __builtin_convertvector(v, bf16n2)); }
; __device__ __forceinline__ f32x16 mfma32(bf16x8 a, bf16x8 b, f32x16 c) { return __builtin_amdgcn_mfma_f32_32x32x16_bf16(a, b, c, 0, 0, 0); }
; __device__ __forceinline__ void chain(Frame& F, int layer, bool sample, int b, int h) {
;     ...
;         v2u sg[4] = {P.sg[0], P.sg[1], P.sg[2], P.sg[3]};
;     ...
;         f32x16 Pn[2] = {zero16(), zero16()};
; #pragma unroll
;         for (int st = 0; st < 4; ++st) { const bf16x8 ka = *(const LAS bf16x8*)(lds + L_KTT + ((32 * kb + l31) * P72 + 16 * st + 8 * hh) * 2);
; #pragma unroll
;             for (int vbi = 0; vbi < 2; ++vbi) { const bf16x8 vbf = *(const LAS bf16x8*)(lds + L_VT + ((32 * (vb0 + vbi) + l31) * P72 + 16 * st + 8 * hh) * 2); Pn[vbi] = mfma32(ka, vbf, Pn[vbi]); } }
; #pragma unroll
;         for (int g = 0; g < 4; ++g) { const f32x4 el = *(const LAS f32x4*)(lds + L_EV + (32 * kb + 8 * g + 4 * hh) * 4), elm = *(const LAS f32x4*)(lds + L_EV + (128 + 32 * kb + 8 * g + 4 * hh) * 4);
; #pragma unroll
;             for (int vbi = 0; vbi < 2; ++vbi) {
; #pragma unroll
;                 for (int j = 0; j < 4; ++j) S[vbi][4 * g + j] = el[j] * S[vbi][4 * g + j] + elm[j] * Pn[vbi][4 * g + j];
;                 v2u w; w.x = cvt_pk_bf16(S[vbi][4 * g], S[vbi][4 * g + 1]); w.y = cvt_pk_bf16(S[vbi][4 * g + 2], S[vbi][4 * g + 3]);
;                 *(LAS v2u*)(lds + L_ST + ((32 * (vb0 + vbi) + l31) * P136 + 32 * kb + 8 * g + 4 * hh) * 2) = w; } }
.LBB0_760:
	s_or_b64 exec, exec, s[64:65]
	v_add_u32_e32 v0, s76, v32
	v_add_u32_e32 v115, s77, v32
	v_mad_u64_u32 v[0:1], s[16:17], v0, s33, v[116:117]
	v_mul_lo_u32 v152, v115, s33
	v_lshl_add_u32 v153, v0, 1, 0
	v_add_u32_e32 v0, v116, v152
	v_lshl_add_u32 v0, v0, 1, s6
	ds_read_b128 v[0:3], v0
	ds_read_b128 v[4:7], v153 offset:52224
	ds_read_b128 v[144:147], v153 offset:52256
	v_add_u32_e32 v154, s4, v32
	v_mul_lo_u32 v155, v154, s33
	s_waitcnt lgkmcnt(1)
	v_mfma_f32_32x32x16_bf16 v[16:31], v[4:7], v[0:3], 0
	v_add_u32_e32 v0, v116, v155
	v_add_u32_e32 v156, 16, v116
	v_lshl_add_u32 v0, v0, 1, s6
	v_add_u32_e32 v148, v156, v152
	ds_read_b128 v[0:3], v0
	v_lshl_add_u32 v148, v148, 1, s6
	ds_read_b128 v[148:151], v148
	s_waitcnt lgkmcnt(1)
	v_mfma_f32_32x32x16_bf16 v[0:15], v[4:7], v[0:3], 0
	v_add_u32_e32 v114, s76, v114
	s_add_i32 s16, 0, 0x21800
	v_mul_lo_u32 v115, v115, s7
	s_add_i32 s15, 0, 0x18000
	s_cmp_eq_u32 s20, s14
	s_mov_b32 s62, s20
	s_waitcnt lgkmcnt(0)
	v_mfma_f32_32x32x16_bf16 v[16:31], v[144:147], v[148:151], v[16:31]
	v_add_u32_e32 v148, v156, v155
	v_lshl_add_u32 v148, v148, 1, s6
	ds_read_b128 v[148:151], v148
	v_add_u32_e32 v156, 32, v116
	v_add_u32_e32 v116, 48, v116
	s_waitcnt lgkmcnt(0)
	v_mfma_f32_32x32x16_bf16 v[0:15], v[144:147], v[148:151], v[0:15]
	ds_read_b128 v[144:147], v153 offset:52288
	v_add_u32_e32 v148, v156, v152
	v_lshl_add_u32 v148, v148, 1, s6
	ds_read_b128 v[148:151], v148
	s_waitcnt lgkmcnt(0)
	v_mfma_f32_32x32x16_bf16 v[16:31], v[144:147], v[148:151], v[16:31]
	v_add_u32_e32 v148, v156, v155
	v_lshl_add_u32 v148, v148, 1, s6
	ds_read_b128 v[148:151], v148
	s_waitcnt lgkmcnt(0)
	v_mfma_f32_32x32x16_bf16 v[0:15], v[144:147], v[148:151], v[0:15]
	ds_read_b128 v[144:147], v153 offset:52320
	v_add_u32_e32 v148, v116, v152
	v_lshl_add_u32 v148, v148, 1, s6
	ds_read_b128 v[148:151], v148
	v_add_u32_e32 v116, v116, v155
	v_lshl_add_u32 v116, v116, 1, s6
	s_waitcnt lgkmcnt(0)
	v_mfma_f32_32x32x16_bf16 v[16:31], v[144:147], v[148:151], v[16:31]
	ds_read_b128 v[148:151], v116
	v_lshl_add_u32 v116, v114, 2, s16
	s_waitcnt lgkmcnt(0)
	v_mfma_f32_32x32x16_bf16 v[0:15], v[144:147], v[148:151], v[0:15]
	ds_read_b128 v[144:147], v116
	ds_read_b128 v[148:151], v116 offset:512
	s_waitcnt lgkmcnt(0)
	s_nop 4
	v_mul_f32_e64 v16, v16, v148
	v_mul_f32_e64 v17, v17, v149
	v_pk_fma_f32 v[64:65], v[64:65], v[144:145], v[16:17]
	s_nop 0
	v_pk_mul_f32 v[0:1], v[0:1], v[148:149]
	v_pk_mul_f32 v[16:17], v[18:19], v[150:151]
	v_pk_fma_f32 v[36:37], v[36:37], v[144:145], v[0:1]
	v_pk_mul_f32 v[0:1], v[2:3], v[150:151]
	v_mul_lo_u32 v144, v154, s7
	v_pk_fma_f32 v[62:63], v[62:63], v[146:147], v[16:17]
	v_add_u32_e32 v18, v114, v115
	v_pk_fma_f32 v[34:35], v[34:35], v[146:147], v[0:1]
	v_add_u32_e32 v2, v114, v144
	v_cvt_pk_bf16_f32 v16, v64, v65
	v_cvt_pk_bf16_f32 v17, v62, v63
	v_lshl_add_u32 v18, v18, 1, s15
	v_cvt_pk_bf16_f32 v0, v36, v37
	v_cvt_pk_bf16_f32 v1, v34, v35
	v_lshl_add_u32 v2, v2, 1, s15
	v_add_u32_e32 v145, 8, v114
	ds_write_b64 v18, v[16:17]
	ds_write_b64 v2, v[0:1]
	v_lshl_add_u32 v0, v145, 2, s16
	ds_read_b128 v[0:3], v0
	ds_read_b128 v[16:19], v116 offset:544
	s_waitcnt lgkmcnt(0)
	v_pk_mul_f32 v[20:21], v[20:21], v[16:17]
	v_pk_mul_f32 v[4:5], v[4:5], v[16:17]
	v_pk_fma_f32 v[60:61], v[60:61], v[0:1], v[20:21]
	v_pk_mul_f32 v[20:21], v[22:23], v[18:19]
	v_pk_fma_f32 v[40:41], v[40:41], v[0:1], v[4:5]
	v_pk_mul_f32 v[0:1], v[6:7], v[18:19]
	v_pk_fma_f32 v[58:59], v[58:59], v[2:3], v[20:21]
	v_add_u32_e32 v22, v145, v115
	v_pk_fma_f32 v[38:39], v[38:39], v[2:3], v[0:1]
	v_add_u32_e32 v2, v145, v144
	v_cvt_pk_bf16_f32 v20, v60, v61
	v_cvt_pk_bf16_f32 v21, v58, v59
	v_lshl_add_u32 v22, v22, 1, s15
	v_cvt_pk_bf16_f32 v0, v40, v41
	v_cvt_pk_bf16_f32 v1, v38, v39
	v_lshl_add_u32 v2, v2, 1, s15
	v_add_u32_e32 v18, 16, v114
	ds_write_b64 v22, v[20:21]
	ds_write_b64 v2, v[0:1]
	v_lshl_add_u32 v0, v18, 2, s16
	ds_read_b128 v[0:3], v0
	ds_read_b128 v[4:7], v116 offset:576
	v_add_u32_e32 v19, v18, v115
	v_lshl_add_u32 v19, v19, 1, s15
	s_waitcnt vmcnt(28)
	v_mov_b64_e32 v[22:23], v[112:113]
	s_waitcnt vmcnt(28)
	v_mov_b64_e32 v[20:21], v[110:111]
	s_waitcnt lgkmcnt(0)
	v_pk_mul_f32 v[16:17], v[24:25], v[4:5]
	v_pk_mul_f32 v[4:5], v[8:9], v[4:5]
	v_pk_fma_f32 v[56:57], v[56:57], v[0:1], v[16:17]
	v_pk_mul_f32 v[16:17], v[26:27], v[6:7]
	v_pk_fma_f32 v[44:45], v[44:45], v[0:1], v[4:5]
	v_pk_mul_f32 v[0:1], v[10:11], v[6:7]
	v_pk_fma_f32 v[54:55], v[54:55], v[2:3], v[16:17]
	v_pk_fma_f32 v[42:43], v[42:43], v[2:3], v[0:1]
	v_add_u32_e32 v2, v18, v144
	v_cvt_pk_bf16_f32 v16, v56, v57
	v_cvt_pk_bf16_f32 v17, v54, v55
	v_cvt_pk_bf16_f32 v0, v44, v45
	v_cvt_pk_bf16_f32 v1, v42, v43
	v_lshl_add_u32 v2, v2, 1, s15
	v_add_u32_e32 v10, 24, v114
	ds_write_b64 v19, v[16:17]
	ds_write_b64 v2, v[0:1]
	v_lshl_add_u32 v0, v10, 2, s16
	ds_read_b128 v[0:3], v0
	ds_read_b128 v[4:7], v116 offset:608
	v_add_u32_e32 v11, v10, v115
	v_lshl_add_u32 v11, v11, 1, s15
	s_waitcnt vmcnt(28)
	v_mov_b64_e32 v[18:19], v[108:109]
	s_waitcnt vmcnt(28)
	v_mov_b64_e32 v[16:17], v[106:107]
	s_waitcnt lgkmcnt(0)
	v_pk_mul_f32 v[8:9], v[28:29], v[4:5]
	v_pk_mul_f32 v[4:5], v[12:13], v[4:5]
	v_pk_fma_f32 v[52:53], v[52:53], v[0:1], v[8:9]
	v_pk_mul_f32 v[8:9], v[30:31], v[6:7]
	v_pk_fma_f32 v[50:51], v[50:51], v[0:1], v[4:5]
	v_pk_mul_f32 v[0:1], v[14:15], v[6:7]
	v_pk_fma_f32 v[46:47], v[46:47], v[2:3], v[8:9]
	v_pk_fma_f32 v[48:49], v[48:49], v[2:3], v[0:1]
	v_add_u32_e32 v2, v10, v144
	v_cvt_pk_bf16_f32 v8, v52, v53
	v_cvt_pk_bf16_f32 v9, v46, v47
	v_cvt_pk_bf16_f32 v0, v50, v51
	v_cvt_pk_bf16_f32 v1, v48, v49
	v_lshl_add_u32 v2, v2, 1, s15
	ds_write_b64 v11, v[8:9]
	ds_write_b64 v2, v[0:1]
	s_cbranch_scc1 .LBB0_819
; #define GAS __attribute__((address_space(1)))
; #define LAS __attribute__((address_space(3)))
;     __device__ __forceinline__ GAS unsigned char* wsp() const { return (GAS unsigned char*)rd(18); }
; template <int PART>
; __device__ __forceinline__ void prefetch(Pre& P, const GAS unsigned char* ws, size_t row0, int nvalid, int seg, int colb  , int trow  , int sgcol  ) {
;     ...
;     if (nvalid == 64) {
; #pragma unroll
;         for (int i = 0; i < 8; ++i) { const unsigned o = (unsigned)((seg * 8 + i) * 1024 + colb);
;             if (PART & 1) P.lf[i] = *(const GAS unsigned*)(LF + o);
; __device__ __forceinline__ void chain(Frame& F, int layer, bool sample, int b, int h) {
;     ...
;     for (int c = 0; c < nchunks; ++c) {
;         asm volatile("" : "+v"(l31), "+v"(hh), "+v"(kp));
;         const int nvalid = min(64, L - 64 * c); const size_t row0 = rowbase + (size_t)64 * c;
;         float c0[8], c1[8]; { float a0 = 0.f, a1 = 0.f;
; #pragma unroll
;             for (int i = 0; i < 8; ++i) { const pg8::h16x2 hv = __builtin_bit_cast(pg8::h16x2, P.lf[i]); a0 += (float)hv.x; a1 += (float)hv.y; c0[i] = a0; c1[i] = a1; }
;             *(LAS f32x2*)(lds + L_SEG + (seg * 128 + 2 * kp) * 4) = (f32x2){a0, a1}; }
;         if (c + 1 < nchunks) prefetch<1>(P, F.wsp(), rowbase + (size_t)64 * (c + 1), min(64, L - 64 * (c + 1)), seg, colb, 32 * otb + l31, h * 128 + 32 * ovb + 4 * hh);
.LBB0_761:
	s_waitcnt vmcnt(32)
	v_cvt_f32_f16_sdwa v1, v95 dst_sel:DWORD dst_unused:UNUSED_PAD src0_sel:WORD_1
	v_cvt_f32_f16_e32 v0, v95
	v_cvt_f32_f16_sdwa v3, v97 dst_sel:DWORD dst_unused:UNUSED_PAD src0_sel:WORD_1
	v_cvt_f32_f16_e32 v2, v97
	v_cvt_f32_f16_sdwa v5, v99 dst_sel:DWORD dst_unused:UNUSED_PAD src0_sel:WORD_1
	v_cvt_f32_f16_e32 v4, v99
	v_cvt_f32_f16_sdwa v7, v103 dst_sel:DWORD dst_unused:UNUSED_PAD src0_sel:WORD_1
	v_cvt_f32_f16_e32 v6, v103
	v_pk_add_f32 v[30:31], v[0:1], 0 op_sel_hi:[1,0]
	v_cvt_f32_f16_sdwa v1, v101 dst_sel:DWORD dst_unused:UNUSED_PAD src0_sel:WORD_1
	v_cvt_f32_f16_e32 v0, v101
	v_pk_add_f32 v[28:29], v[30:31], v[2:3]
	v_cvt_f32_f16_sdwa v3, v117 dst_sel:DWORD dst_unused:UNUSED_PAD src0_sel:WORD_1
	v_cvt_f32_f16_e32 v2, v117
	v_pk_add_f32 v[26:27], v[28:29], v[4:5]
	v_cvt_f32_f16_sdwa v5, v118 dst_sel:DWORD dst_unused:UNUSED_PAD src0_sel:WORD_1
	v_cvt_f32_f16_e32 v4, v118
	v_pk_add_f32 v[24:25], v[26:27], v[6:7]
	v_cvt_f32_f16_sdwa v7, v129 dst_sel:DWORD dst_unused:UNUSED_PAD src0_sel:WORD_1
	v_cvt_f32_f16_e32 v6, v129
	v_pk_add_f32 v[14:15], v[24:25], v[0:1]
	s_add_i32 s20, s62, 1
	v_pk_add_f32 v[12:13], v[14:15], v[2:3]
	s_cmp_lt_u32 s20, s14
	v_pk_add_f32 v[10:11], v[12:13], v[4:5]
	v_lshlrev_b32_e32 v2, 3, v93
	v_pk_add_f32 v[8:9], v[10:11], v[6:7]
	v_add_u32_e32 v0, s22, v2
	s_cselect_b64 s[64:65], -1, 0
	s_cmp_ge_u32 s20, s14
	ds_write_b64 v0, v[8:9]
	s_cbranch_scc1 .Lch_skipL
	v_mov_b32_e32 v0, s18
	ds_read_b64 v[0:1], v0
	s_lshl_b32 s15, s20, 6
	s_sub_i32 s15, s13, s15
	s_lshl_b64 s[16:17], s[20:21], 17
	s_waitcnt lgkmcnt(0)
	v_readfirstlane_b32 s25, v0
	v_readfirstlane_b32 s24, v1
	s_add_u32 s16, s25, s16
	s_addc_u32 s17, s24, s17
	s_add_u32 s16, s16, s58
	s_addc_u32 s17, s17, s59
	s_add_u32 s66, s16, 0x24600000
	s_addc_u32 s67, s17, 0
	s_cmp_gt_i32 s15, 63
	s_cbranch_scc1 .LBB0_771
	s_min_i32 s15, s15, 64
	s_cmp_lt_i32 s23, s15
	s_cbranch_scc0 .LBB0_772
	v_lshl_add_u64 v[0:1], v[66:67], 1, s[66:67]
	global_load_dword v95, v[0:1], off
	s_cmp_ge_i32 s28, s15
	s_cbranch_scc0 .LBB0_773

; #define GAS __attribute__((address_space(1)))
; template <int PART>
; __device__ __forceinline__ void prefetch(Pre& P, const GAS unsigned char* ws, size_t row0, int nvalid, int seg, int colb  , int trow  , int sgcol  ) {
;     ...
; #pragma unroll
;         for (int i = 0; i < 8; ++i) { const int t = seg * 8 + i; const unsigned o = (unsigned)(t * 1024 + colb);
;             if (t < nvalid) { if (PART & 1) P.lf[i] = *(const GAS unsigned*)(LF + o); if (PART & 2) { P.q[i] = *(const GAS unsigned*)(QC + o); P.k[i] = *(const GAS unsigned*)(KC + o); P.v[i] = *(const GAS unsigned*)(IC + o); } }
;             else { if (PART & 1) P.lf[i] = 0u; if (PART & 2) { P.q[i] = 0u; P.k[i] = 0u; P.v[i] = 0u; } } }
.LBB0_779:
	s_waitcnt vmcnt(0)
	s_cmp_lt_i32 s31, s15
	s_cselect_b64 s[68:69], -1, 0
	v_mov_b64_e32 v[0:1], v[104:105]
	s_branch .LBB0_781

; #define LAS __attribute__((address_space(3)))
; __device__ __forceinline__ void chain(Frame& F, int layer, bool sample, int b, int h) {
;     ...
;         HG_BAR();
;         float off0 = 0.f, off1 = 0.f, m0 = 0.f, m1 = 0.f, la0 = 0.f, la1 = 0.f;
; #pragma unroll
;         for (int s = 0; s < 8; ++s) { const f32x2 tt = *(const LAS f32x2*)(lds + L_SEG + (s * 128 + 2 * kp) * 4);
;             if (s < seg) { off0 += tt.x; off1 += tt.y; } if (s < 4) { m0 += tt.x; m1 += tt.y; } la0 += tt.x; la1 += tt.y; }
;         unsigned ktt0[8], ktt1[8], vt0[8], vt1[8]; const float e2m0 = fexp2(m0), e2m1 = fexp2(m1);
; #pragma unroll
;         for (int i = 0; i < 8; ++i) { const int t = seg * 8 + i; const float cu0 = off0 + c0[i], cu1 = off1 + c1[i];
;             const float q0 = bf_lo(P.q[i]), q1 = bf_hi(P.q[i]), k0 = bf_lo(P.k[i]), k1 = bf_hi(P.k[i]);
;             const float em0 = fexp2(cu0 - m0), em1 = fexp2(cu1 - m1), ek0 = fexp2(m0 - cu0), ek1 = fexp2(m1 - cu1), eq0 = em0 * e2m0, eq1 = em1 * e2m1;
;             *(LAS unsigned*)(lds + L_QS + (t * P136 + 2 * kp) * 2) = cvt_pk_bf16(q0 * eq0, q1 * eq1);
;             *(LAS unsigned*)(lds + L_QT + (t * P136 + 2 * kp) * 2) = cvt_pk_bf16(q0 * em0, q1 * em1);
;             const unsigned kt = cvt_pk_bf16(k0 * ek0, k1 * ek1);
;             *(LAS unsigned*)(lds + L_KT + (t * P136 + 2 * kp) * 2) = kt;
;             ktt0[i] = kt & 0xffffu; ktt1[i] = kt >> 16; vt0[i] = P.v[i] & 0xffffu; vt1[i] = P.v[i] >> 16; }
;         { v4u w; w.x = ktt0[0] | (ktt0[1] << 16); w.y = ktt0[2] | (ktt0[3] << 16); w.z = ktt0[4] | (ktt0[5] << 16); w.w = ktt0[6] | (ktt0[7] << 16);
;           *(LAS v4u*)(lds + L_KTT + ((2 * kp) * P72 + 8 * seg) * 2) = w;
;           w.x = ktt1[0] | (ktt1[1] << 16); w.y = ktt1[2] | (ktt1[3] << 16); w.z = ktt1[4] | (ktt1[5] << 16); w.w = ktt1[6] | (ktt1[7] << 16);
;           *(LAS v4u*)(lds + L_KTT + ((2 * kp + 1) * P72 + 8 * seg) * 2) = w;
;           w.x = vt0[0] | (vt0[1] << 16); w.y = vt0[2] | (vt0[3] << 16); w.z = vt0[4] | (vt0[5] << 16); w.w = vt0[6] | (vt0[7] << 16);
;           *(LAS v4u*)(lds + L_VT + ((2 * kp) * P72 + 8 * seg) * 2) = w;
;           w.x = vt1[0] | (vt1[1] << 16); w.y = vt1[2] | (vt1[3] << 16); w.z = vt1[4] | (vt1[5] << 16); w.w = vt1[6] | (vt1[7] << 16);
;           *(LAS v4u*)(lds + L_VT + ((2 * kp + 1) * P72 + 8 * seg) * 2) = w; }
.LBB0_784:
	v_add_u32_e32 v110, 0, v2
	s_waitcnt lgkmcnt(0)
	s_barrier
	v_add_u32_e32 v4, 0x20800, v110
	ds_read2st64_b64 v[0:3], v4 offset1:1
	ds_read2st64_b64 v[106:109], v4 offset0:2 offset1:3
	v_mov_b32_e32 v114, v31
	s_movk_i32 s15, 0x90
	v_and_b32_e32 v155, 0xffff, v127
	s_waitcnt lgkmcnt(1)
	v_add_f32_e32 v0, 0, v0
	v_add_f32_e32 v1, 0, v1
	v_cndmask_b32_e64 v5, v1, 0, s[10:11]
	v_cndmask_b32_e64 v6, v0, 0, s[10:11]
	v_add_f32_e32 v7, v2, v6
	v_add_f32_e32 v111, v3, v5
	v_cndmask_b32_e64 v5, v5, v111, s[38:39]
	v_cndmask_b32_e64 v6, v6, v7, s[38:39]
	v_add_f32_e32 v0, v0, v2
	v_add_f32_e32 v1, v1, v3
	s_waitcnt lgkmcnt(0)
	v_add_f32_e32 v2, v106, v6
	v_add_f32_e32 v3, v107, v5
	v_cndmask_b32_e64 v5, v5, v3, s[40:41]
	v_cndmask_b32_e64 v6, v6, v2, s[40:41]
	v_add_f32_e32 v113, v0, v106
	v_add_f32_e32 v115, v1, v107
	ds_read2st64_b64 v[0:3], v4 offset0:4 offset1:5
	v_add_f32_e32 v7, v108, v6
	v_add_f32_e32 v106, v109, v5
	v_cndmask_b32_e64 v106, v5, v106, s[42:43]
	v_cndmask_b32_e64 v107, v6, v7, s[42:43]
	ds_read2st64_b64 v[4:7], v4 offset0:6 offset1:7
	s_waitcnt lgkmcnt(1)
	v_add_f32_e32 v111, v0, v107
	v_add_f32_e32 v112, v1, v106
	v_cndmask_b32_e64 v106, v106, v112, s[44:45]
	v_cndmask_b32_e64 v107, v107, v111, s[44:45]
	v_add_f32_e32 v111, v2, v107
	v_add_f32_e32 v112, v3, v106
	v_cndmask_b32_e64 v106, v106, v112, s[46:47]
	v_cndmask_b32_e64 v107, v107, v111, s[46:47]
	s_waitcnt lgkmcnt(0)
	v_add_f32_e32 v111, v4, v107
	v_add_f32_e32 v112, v5, v106
	v_cndmask_b32_e64 v106, v106, v112, s[48:49]
	v_cndmask_b32_e64 v107, v107, v111, s[48:49]
	v_add_f32_e32 v111, v6, v107
	v_add_f32_e32 v112, v7, v106
	v_cndmask_b32_e64 v144, v106, v112, s[50:51]
	v_cndmask_b32_e64 v146, v107, v111, s[50:51]
	v_mov_b32_e32 v112, v30
	v_mov_b32_e32 v147, v108
	v_pk_add_f32 v[106:107], v[112:113], v[146:147]
	v_mov_b32_e32 v145, v109
	v_pk_add_f32 v[30:31], v[114:115], v[144:145]
	v_sub_f32_e32 v111, v106, v107
	v_exp_f32_e32 v148, v111
	v_sub_f32_e32 v111, v30, v31
	v_exp_f32_e32 v108, v107
	v_exp_f32_e32 v109, v31
	v_exp_f32_e32 v149, v111
	v_sub_f32_e32 v106, v107, v106
	v_sub_f32_e32 v30, v31, v30
	v_exp_f32_e32 v150, v106
	v_exp_f32_e32 v151, v30
	s_waitcnt vmcnt(12)
	v_lshlrev_b32_e32 v112, 16, v120
	v_and_b32_e32 v113, 0xffff0000, v120
	v_pk_mul_f32 v[152:153], v[108:109], v[148:149]
	s_waitcnt vmcnt(12)
	v_lshlrev_b32_e32 v114, 16, v121
	v_and_b32_e32 v115, 0xffff0000, v121
	v_pk_mul_f32 v[152:153], v[152:153], v[112:113]
	v_pk_mul_f32 v[112:113], v[148:149], v[112:113]
	v_add_f32_e32 v148, v28, v146
	v_add_f32_e32 v149, v29, v144
	v_cvt_pk_bf16_f32 v111, v112, v113
	v_pk_mul_f32 v[112:113], v[150:151], v[114:115]
	v_sub_f32_e32 v114, v148, v107
	v_sub_f32_e32 v115, v149, v31
	v_exp_f32_e32 v114, v114
	v_exp_f32_e32 v115, v115
	v_sub_f32_e32 v148, v107, v148
	v_sub_f32_e32 v149, v31, v149
	v_lshlrev_b32_e32 v28, 16, v119
	v_and_b32_e32 v29, 0xffff0000, v119
	v_exp_f32_e32 v148, v148
	v_exp_f32_e32 v149, v149
	v_pk_mul_f32 v[150:151], v[108:109], v[114:115]
	v_cvt_pk_bf16_f32 v30, v152, v153
	v_pk_mul_f32 v[150:151], v[150:151], v[28:29]
	v_lshl_add_u32 v106, v93, 2, s5
	v_cvt_pk_bf16_f32 v150, v150, v151
	v_pk_mul_f32 v[28:29], v[114:115], v[28:29]
	v_cvt_pk_bf16_f32 v116, v112, v113
	v_lshlrev_b32_e32 v112, 16, v124
	v_and_b32_e32 v113, 0xffff0000, v124
	ds_write2_b32 v106, v30, v150 offset1:68
	v_cvt_pk_bf16_f32 v28, v28, v29
	v_add_u32_e32 v30, 0x4400, v106
	v_add_f32_e32 v114, v26, v146
	v_add_f32_e32 v115, v27, v144
	ds_write2_b32 v30, v111, v28 offset1:68
	v_pk_mul_f32 v[28:29], v[148:149], v[112:113]
	v_sub_f32_e32 v112, v114, v107
	v_sub_f32_e32 v113, v115, v31
	v_exp_f32_e32 v112, v112
	v_exp_f32_e32 v113, v113
	v_sub_f32_e32 v114, v107, v114
	v_sub_f32_e32 v115, v31, v115
	v_exp_f32_e32 v114, v114
	v_exp_f32_e32 v115, v115
	v_lshlrev_b32_e32 v26, 16, v125
	v_and_b32_e32 v27, 0xffff0000, v125
	v_pk_mul_f32 v[148:149], v[108:109], v[112:113]
	v_cvt_pk_bf16_f32 v111, v28, v29
	v_add_u32_e32 v150, 0x8800, v106
	v_lshlrev_b32_e32 v28, 16, v126
	v_and_b32_e32 v29, 0xffff0000, v126
	v_pk_mul_f32 v[148:149], v[148:149], v[26:27]
	v_pk_mul_f32 v[26:27], v[112:113], v[26:27]
	v_add_f32_e32 v112, v24, v146
	v_add_f32_e32 v113, v25, v144
	v_and_b32_e32 v145, 0xffff, v116
	v_lshrrev_b32_e32 v147, 16, v116
	ds_write2_b32 v150, v116, v111 offset1:68
	v_cvt_pk_bf16_f32 v116, v148, v149
	v_cvt_pk_bf16_f32 v148, v26, v27
	v_pk_mul_f32 v[26:27], v[114:115], v[28:29]
	v_sub_f32_e32 v28, v112, v107
	v_sub_f32_e32 v29, v113, v31
	v_exp_f32_e32 v28, v28
	v_exp_f32_e32 v29, v29
	v_sub_f32_e32 v112, v107, v112
	v_sub_f32_e32 v113, v31, v113
	v_exp_f32_e32 v112, v112
	v_exp_f32_e32 v113, v113
	v_lshlrev_b32_e32 v24, 16, v128
	v_and_b32_e32 v25, 0xffff0000, v128
	v_pk_mul_f32 v[114:115], v[108:109], v[28:29]
	v_cvt_pk_bf16_f32 v149, v26, v27
	v_pk_mul_f32 v[114:115], v[114:115], v[24:25]
	v_pk_mul_f32 v[24:25], v[28:29], v[24:25]
	v_lshlrev_b32_e32 v26, 16, v131
	v_and_b32_e32 v27, 0xffff0000, v131
	v_cvt_pk_bf16_f32 v24, v24, v25
	v_add_f32_e32 v28, v14, v146
	v_add_f32_e32 v29, v15, v144
	ds_write2_b32 v30, v148, v24 offset0:136 offset1:204
	v_pk_mul_f32 v[24:25], v[112:113], v[26:27]
	v_sub_f32_e32 v26, v28, v107
	v_sub_f32_e32 v27, v29, v31
	v_exp_f32_e32 v26, v26
	v_exp_f32_e32 v27, v27
	v_sub_f32_e32 v28, v107, v28
	v_sub_f32_e32 v29, v31, v29
	v_exp_f32_e32 v28, v28
	v_exp_f32_e32 v29, v29
	v_lshlrev_b32_e32 v14, 16, v134
	v_and_b32_e32 v15, 0xffff0000, v134
	v_pk_mul_f32 v[112:113], v[108:109], v[26:27]
	v_cvt_pk_bf16_f32 v30, v24, v25
	v_lshlrev_b32_e32 v24, 16, v133
	v_and_b32_e32 v25, 0xffff0000, v133
	v_pk_mul_f32 v[112:113], v[112:113], v[14:15]
; #define GAS __attribute__((address_space(1)))
; template <int PART>
; __device__ __forceinline__ void prefetch(Pre& P, const GAS unsigned char* ws, size_t row0, int nvalid, int seg, int colb  , int trow  , int sgcol  ) {
;     const GAS _Float16* LF = (const GAS _Float16*)(ws + WS_LOGF) + row0 * 1024; const GAS bf16* QC = (const GAS bf16*)(ws + WS_QC) + row0 * 1024; const GAS bf16* KC = (const GAS bf16*)(ws + WS_KC) + row0 * 1024; const GAS bf16* IC = (const GAS bf16*)(ws + WS_IC) + row0 * 1024;
;     if (PART & 2) { const GAS bf16* SGC = (const GAS bf16*)(ws + WS_SGC) + row0 * 1024; const unsigned so = (unsigned)((trow < nvalid ? trow : 0) * 1024 + sgcol);
; #pragma unroll
;       for (int g = 0; g < 4; ++g) P.sg[g] = *(const GAS v2u*)(SGC + so + 8 * g); }
;     if (nvalid == 64) {
; #pragma unroll
;         for (int i = 0; i < 8; ++i) { const unsigned o = (unsigned)((seg * 8 + i) * 1024 + colb);
;             if (PART & 1) P.lf[i] = *(const GAS unsigned*)(LF + o);
; __device__ __forceinline__ void chain(Frame& F, int layer, bool sample, int b, int h) {
;     ...
;         { v4u w; w.x = ktt0[0] | (ktt0[1] << 16); w.y = ktt0[2] | (ktt0[3] << 16); w.z = ktt0[4] | (ktt0[5] << 16); w.w = ktt0[6] | (ktt0[7] << 16);
;           *(LAS v4u*)(lds + L_KTT + ((2 * kp) * P72 + 8 * seg) * 2) = w;
;           w.x = ktt1[0] | (ktt1[1] << 16); w.y = ktt1[2] | (ktt1[3] << 16); w.z = ktt1[4] | (ktt1[5] << 16); w.w = ktt1[6] | (ktt1[7] << 16);
;           *(LAS v4u*)(lds + L_KTT + ((2 * kp + 1) * P72 + 8 * seg) * 2) = w;
;           w.x = vt0[0] | (vt0[1] << 16); w.y = vt0[2] | (vt0[3] << 16); w.z = vt0[4] | (vt0[5] << 16); w.w = vt0[6] | (vt0[7] << 16);
;           *(LAS v4u*)(lds + L_VT + ((2 * kp) * P72 + 8 * seg) * 2) = w;
;           w.x = vt1[0] | (vt1[1] << 16); w.y = vt1[2] | (vt1[3] << 16); w.z = vt1[4] | (vt1[5] << 16); w.w = vt1[6] | (vt1[7] << 16);
;           *(LAS v4u*)(lds + L_VT + ((2 * kp + 1) * P72 + 8 * seg) * 2) = w; }
;         if (seg == 0) { *(LAS f32x2*)(lds + L_EV + (2 * kp) * 4) = (f32x2){fexp2(la0), fexp2(la1)}; *(LAS f32x2*)(lds + L_EV + (128 + 2 * kp) * 4) = (f32x2){fexp2(la0 - m0), fexp2(la1 - m1)}; }
;         v2u sg[4] = {P.sg[0], P.sg[1], P.sg[2], P.sg[3]};
;         if (c + 1 < nchunks) prefetch<2>(P, F.wsp(), rowbase + (size_t)64 * (c + 1), min(64, L - 64 * (c + 1)), seg, colb, 32 * otb + l31, h * 128 + 32 * ovb + 4 * hh);
	v_pk_mul_f32 v[14:15], v[26:27], v[14:15]
	v_add_f32_e32 v26, v12, v146
	v_add_f32_e32 v27, v13, v144
	v_cvt_pk_bf16_f32 v112, v112, v113
	v_cvt_pk_bf16_f32 v113, v14, v15
	v_pk_mul_f32 v[14:15], v[28:29], v[24:25]
	v_sub_f32_e32 v24, v26, v107
	v_sub_f32_e32 v25, v27, v31
	v_exp_f32_e32 v24, v24
	v_exp_f32_e32 v25, v25
	v_sub_f32_e32 v26, v107, v26
	v_sub_f32_e32 v27, v31, v27
	v_lshlrev_b32_e32 v12, 16, v135
	v_and_b32_e32 v13, 0xffff0000, v135
	v_exp_f32_e32 v26, v26
	v_exp_f32_e32 v27, v27
	v_pk_mul_f32 v[28:29], v[108:109], v[24:25]
	v_cvt_pk_bf16_f32 v114, v114, v115
	v_pk_mul_f32 v[28:29], v[28:29], v[12:13]
	v_pk_mul_f32 v[12:13], v[24:25], v[12:13]
	v_cvt_pk_bf16_f32 v28, v28, v29
	v_add_u32_e32 v29, 0x400, v106
	ds_write2_b32 v106, v116, v114 offset0:136 offset1:204
	v_cvt_pk_bf16_f32 v114, v14, v15
	v_lshlrev_b32_e32 v14, 16, v137
	v_and_b32_e32 v15, 0xffff0000, v137
	ds_write2_b32 v29, v112, v28 offset0:16 offset1:84
	v_cvt_pk_bf16_f32 v12, v12, v13
	v_add_u32_e32 v28, 0x4800, v106
	v_add_f32_e32 v24, v10, v146
	v_add_f32_e32 v25, v11, v144
	ds_write2_b32 v28, v113, v12 offset0:16 offset1:84
	v_pk_mul_f32 v[12:13], v[26:27], v[14:15]
	v_sub_f32_e32 v14, v24, v107
	v_sub_f32_e32 v15, v25, v31
	v_exp_f32_e32 v14, v14
	v_exp_f32_e32 v15, v15
	v_sub_f32_e32 v24, v107, v24
	v_sub_f32_e32 v25, v31, v25
	v_exp_f32_e32 v24, v24
	v_exp_f32_e32 v25, v25
	v_lshlrev_b32_e32 v10, 16, v138
	v_and_b32_e32 v11, 0xffff0000, v138
	v_pk_mul_f32 v[26:27], v[108:109], v[14:15]
	v_cvt_pk_bf16_f32 v112, v12, v13
	v_lshlrev_b32_e32 v12, 16, v139
	v_and_b32_e32 v13, 0xffff0000, v139
	v_pk_mul_f32 v[26:27], v[26:27], v[10:11]
	v_pk_mul_f32 v[10:11], v[14:15], v[10:11]
	v_add_f32_e32 v14, v8, v146
	v_add_f32_e32 v15, v9, v144
	v_cvt_pk_bf16_f32 v26, v26, v27
	v_cvt_pk_bf16_f32 v27, v10, v11
	v_pk_mul_f32 v[10:11], v[24:25], v[12:13]
	v_sub_f32_e32 v12, v14, v107
	v_sub_f32_e32 v13, v15, v31
	v_exp_f32_e32 v12, v12
	v_exp_f32_e32 v13, v13
	v_sub_f32_e32 v14, v107, v14
	v_sub_f32_e32 v15, v31, v15
	v_exp_f32_e32 v14, v14
	v_exp_f32_e32 v15, v15
	v_lshlrev_b32_e32 v8, 16, v141
	v_and_b32_e32 v9, 0xffff0000, v141
	v_pk_mul_f32 v[24:25], v[108:109], v[12:13]
	v_cvt_pk_bf16_f32 v113, v10, v11
	v_pk_mul_f32 v[24:25], v[24:25], v[8:9]
	v_pk_mul_f32 v[8:9], v[12:13], v[8:9]
	v_lshlrev_b32_e32 v10, 16, v142
	v_and_b32_e32 v11, 0xffff0000, v142
	v_cvt_pk_bf16_f32 v8, v8, v9
	v_add_u32_e32 v106, 0x8c00, v106
	ds_write2_b32 v28, v27, v8 offset0:152 offset1:220
	v_pk_mul_f32 v[8:9], v[14:15], v[10:11]
	v_mul_lo_u32 v13, v93, s15
	v_and_b32_e32 v151, 0xffff, v149
	v_and_b32_e32 v115, 0xffff, v114
	v_lshrrev_b32_e32 v116, 16, v114
	ds_write2_b32 v106, v114, v112 offset0:16 offset1:84
	v_and_b32_e32 v114, 0xffff, v113
	v_cvt_pk_bf16_f32 v12, v8, v9
	v_add_lshl_u32 v13, v13, s23, 1
	ds_write2_b32 v150, v149, v30 offset0:136 offset1:204
	v_lshrrev_b32_e32 v150, 16, v113
	v_cvt_pk_bf16_f32 v24, v24, v25
	v_lshl_or_b32 v8, v111, 16, v145
	v_lshl_or_b32 v9, v30, 16, v151
	v_lshl_or_b32 v10, v112, 16, v115
	v_lshl_or_b32 v11, v12, 16, v114
	v_add_u32_e32 v14, 0, v13
	v_lshrrev_b32_e32 v154, 16, v149
	ds_write2_b32 v29, v26, v24 offset0:152 offset1:220
	ds_write2_b32 v106, v113, v12 offset0:152 offset1:220
	ds_write_b128 v14, v[8:11] offset:52224
	v_and_or_b32 v11, v12, s19, v150
	v_add_u32_e32 v12, 0x90, v13
	s_waitcnt vmcnt(12)
	v_and_b32_e32 v152, 0xffff, v122
	v_and_b32_e32 v148, 0xffff, v132
	v_and_b32_e32 v157, 0xffff, v140
	v_and_or_b32 v8, v111, s19, v147
	v_and_or_b32 v9, v30, s19, v154
	v_and_or_b32 v10, v112, s19, v116
	v_add_u32_e32 v14, 0, v12
	v_lshrrev_b32_e32 v153, 16, v122
	v_lshrrev_b32_e32 v156, 16, v127
	v_lshrrev_b32_e32 v149, 16, v132
	v_lshrrev_b32_e32 v158, 16, v140
	ds_write_b128 v14, v[8:11] offset:52224
	v_lshl_or_b32 v8, v123, 16, v152
	v_lshl_or_b32 v9, v130, 16, v155
	v_lshl_or_b32 v10, v136, 16, v148
	v_lshl_or_b32 v11, v143, 16, v157
	v_add_u32_e32 v13, s6, v13
	ds_write_b128 v13, v[8:11]
	v_and_or_b32 v8, v123, s19, v153
	v_and_or_b32 v9, v130, s19, v156
	v_and_or_b32 v10, v136, s19, v149
	v_and_or_b32 v11, v143, s19, v158
	v_add_u32_e32 v12, s6, v12
	s_and_b64 vcc, exec, s[54:55]
	ds_write_b128 v12, v[8:11]
	s_cbranch_vccnz .LBB0_786
	v_add_f32_e32 v1, v31, v1
	v_add_f32_e32 v0, v107, v0
	v_add_f32_e32 v1, v1, v3
	v_add_f32_e32 v0, v0, v2
	v_add_f32_e32 v1, v1, v5
	v_add_f32_e32 v0, v0, v4
	v_add_f32_e32 v3, v1, v7
	v_add_f32_e32 v2, v0, v6
	v_sub_f32_e32 v0, v2, v107
	v_sub_f32_e32 v1, v3, v31
	v_exp_f32_e32 v0, v0
	v_exp_f32_e32 v1, v1
	v_exp_f32_e32 v2, v2
	v_exp_f32_e32 v3, v3
	v_add_u32_e32 v4, 0x21800, v110
	ds_write2st64_b64 v4, v[2:3], v[0:1] offset1:1
.LBB0_786:
	s_andn2_b64 vcc, exec, s[64:65]
	v_add_u32_e32 v24, s94, v32
	v_lshlrev_b32_e32 v114, 2, v33
	s_waitcnt vmcnt(12)
	v_mov_b64_e32 v[106:107], v[16:17]
	s_waitcnt vmcnt(12)
	v_mov_b64_e32 v[108:109], v[18:19]
	s_waitcnt vmcnt(12)
	v_mov_b64_e32 v[110:111], v[20:21]
	v_mov_b64_e32 v[112:113], v[22:23]
	s_cbranch_vccnz .LBB0_807
	v_mov_b32_e32 v0, s18
	ds_read_b64 v[0:1], v0
	s_lshl_b32 s15, s20, 6
	s_sub_i32 s24, s13, s15
	s_min_i32 s15, s24, 64
	s_lshl_b64 s[16:17], s[20:21], 16
	s_add_u32 s16, s16, s56
	s_addc_u32 s17, s17, s57
	s_waitcnt lgkmcnt(0)
	v_readfirstlane_b32 s25, v1
	v_readfirstlane_b32 s52, v0
	s_lshl_b64 s[16:17], s[16:17], 1
	v_lshlrev_b32_e32 v1, 10, v24
	v_cmp_gt_i32_e32 vcc, s15, v24
	v_lshlrev_b32_e32 v0, 2, v33
	s_add_u32 s16, s52, s16
	v_cndmask_b32_e32 v1, 0, v1, vcc
	v_add3_u32 v172, v0, s74, v1
	s_addc_u32 s17, s25, s17
	v_lshl_add_u64 v[0:1], v[172:173], 1, s[16:17]
	s_mov_b64 s[52:53], 0x1b400000
	s_mov_b32 s25, 0x1b400000
	v_lshl_add_u64 v[2:3], v[0:1], 0, s[52:53]
	v_add_co_u32_e32 v0, vcc, s25, v0
	s_add_u32 s68, s16, 0x16b00000
	s_nop 0
	v_addc_co_u32_e32 v1, vcc, 0, v1, vcc
	global_load_dwordx2 v[112:113], v[0:1], off
	global_load_dwordx2 v[110:111], v[2:3], off offset:16
	global_load_dwordx2 v[108:109], v[2:3], off offset:32
	global_load_dwordx2 v[106:107], v[2:3], off offset:48
	s_addc_u32 s69, s17, 0
	s_add_u32 s66, s16, 0x14680000
	s_addc_u32 s67, s17, 0
	s_add_u32 s64, s16, 0x18f80000
	s_addc_u32 s65, s17, 0
	s_cmp_gt_i32 s24, 63
	s_cbranch_scc1 .LBB0_803
	v_mov_b32_e32 v119, 0
	s_cmp_lt_i32 s23, s15
	v_mov_b32_e32 v120, 0
	v_mov_b32_e32 v121, 0
	v_mov_b32_e32 v122, 0
	s_cbranch_scc0 .LBB0_790
	v_lshl_add_u64 v[0:1], s[68:69], 0, v[90:91]
	v_lshl_add_u64 v[2:3], s[66:67], 0, v[90:91]
	v_lshl_add_u64 v[4:5], s[64:65], 0, v[90:91]
	global_load_dword v120, v[0:1], off
	global_load_dword v121, v[2:3], off
	global_load_dword v122, v[4:5], off

; #define GAS __attribute__((address_space(1)))
; template <int PART>
; __device__ __forceinline__ void prefetch(Pre& P, const GAS unsigned char* ws, size_t row0, int nvalid, int seg, int colb  , int trow  , int sgcol  ) {
;     ...
; #pragma unroll
;         for (int i = 0; i < 8; ++i) { const int t = seg * 8 + i; const unsigned o = (unsigned)(t * 1024 + colb);
;             if (t < nvalid) { if (PART & 1) P.lf[i] = *(const GAS unsigned*)(LF + o); if (PART & 2) { P.q[i] = *(const GAS unsigned*)(QC + o); P.k[i] = *(const GAS unsigned*)(KC + o); P.v[i] = *(const GAS unsigned*)(IC + o); } }
;             else { if (PART & 1) P.lf[i] = 0u; if (PART & 2) { P.q[i] = 0u; P.k[i] = 0u; P.v[i] = 0u; } } }
.LBB0_802:
	s_waitcnt vmcnt(0)
	s_cmp_lt_i32 s31, s15
	s_cselect_b64 s[70:71], -1, 0
	v_mov_b64_e32 v[0:1], v[104:105]
	s_branch .LBB0_805

; #define GAS __attribute__((address_space(1)))
; __device__ __forceinline__ int lane_id() { unsigned z = 0u; asm volatile("" : "+v"(z)); return (int)__builtin_amdgcn_mbcnt_hi(~0u, __builtin_amdgcn_mbcnt_lo(~0u, z)); }
;     const int wid = wave_id, lane = lane_id(), tid = wid * 64 + lane; const int wr = wid >> 2, wc = wid & 3, fr = lane & 15, fq = lane >> 4;
;     const int K = g.K;
;     unsigned voffA[2], voffB[2];
; #pragma unroll
;     for (int i = 0; i < 2; ++i) { int R, C; stage_rc(tid * 16 + i * 8192, R, C); const int Rb = (R & ~31) + perm32(R & 31);
;         voffA[i] = (unsigned)(R * K + C) * 2u; voffB[i] = (unsigned)(Rb * K + C) * 2u; }
;     const size_t kstep = (size_t)(BK * 2);
;     const size_t hstep = (size_t)HALF * K * 2;
;     const size_t tstep = 2 * hstep;
;     const unsigned ldsw = (unsigned)wid * 1024u;
;     const int aoff = lds_byte(wr * 64 + fr, fq * 8), boff = lds_byte(wc * 32 + fr, fq * 8);
;     ...
;     Unit cur, nxt; int ui = 0;
;     if (!S.template next<MODE>(0, cur)) return;
;     Acc acc;
; #pragma unroll
;     for (int a = 0; a < 2; ++a)
; #pragma unroll
;         for (int b = 0; b < 2; ++b)
; #pragma unroll
;             for (int m = 0; m < 4; ++m)
; #pragma unroll
;                 for (int n = 0; n < 2; ++n) acc[a][b][m][n] = (f32x4){0.f, 0.f, 0.f, 0.f};
;     bf16x8 At[4][2], B0[2][2], B1[2][2];
;     const GAS char* cA = (const GAS char*)(g.A + (size_t)cur.seg * g.a_seg) + (size_t)cur.pm * tstep + (MODE ? (size_t)cur.k0 * kstep : 0); const GAS char* cB = (const GAS char*)(g.Bt + (size_t)cur.seg * g.b_seg) + (size_t)cur.pn * tstep + (MODE ? (size_t)cur.k0 * kstep : 0);
;     PG8_STAGE(PG8_SB(0, 0), cB, voffB); PG8_STAGE(PG8_SB(0, 1), cB + hstep, voffB); PG8_STAGE(PG8_SA(0, 0), cA, voffA); PG8_STAGE(PG8_SA(0, 1), cA + hstep, voffA);
;     if (wr == 1) PG8_BAR;
;     PG8_WAIT_V(2); PG8_BAR;
;     PG8_STAGE(PG8_SB(1, 0), cB + kstep, voffB); PG8_STAGE(PG8_SA(1, 0), cA + kstep, voffA); PG8_STAGE(PG8_SB(1, 1), cB + hstep + kstep, voffB);
; __global__ void __launch_bounds__(512, 2) mega_fwd(Params p) {
;     ...
;         if (IN(pb + 3)) { pg8::Gemm g{(const GAS bf16*)(F.wsp() + WS_Y), (const GAS bf16*)(F.wsp() + WS_WBR) + (size_t)l * 3 * D * D, (size_t)MTOT * 1024, (size_t)D * D, MTOT / 256, D / 256, 3, D, MERGE_TAIL, WGM_SQ};
;             pg8::Order S; S.init(g, F.G, (int)blockIdx.x);
;             pg8::EpiMerge E{F.wsp()};
.Lmr_pre:
	v_mov_b32_e32 v0, s18
	ds_read_b64 v[0:1], v0
	v_readlane_b32 s12, v242, 56
	v_readlane_b32 s13, v242, 57
	s_andn2_b64 vcc, exec, s[12:13]
	s_waitcnt lgkmcnt(0)
	v_readfirstlane_b32 s9, v1
	v_cndmask_b32_e64 v1, 0, 1, s[12:13]
	v_readfirstlane_b32 s8, v0
	v_mov_b32_e32 v0, v173
	v_cmp_ne_u32_e64 s[56:57], 1, v1
	s_cbranch_vccnz .LBB0_934
	v_readlane_b32 s12, v242, 62
	s_mov_b32 s52, s12
	v_readlane_b32 s12, v242, 63
	s_mov_b32 s60, s12
.LBB0_934:
	v_readlane_b32 s12, v240, 8
	s_add_u32 s14, s8, 0x28f00000
	v_readlane_b32 s13, v240, 9
	s_mul_i32 s20, s12, 0x300000
	s_addc_u32 s15, s9, 0
	s_lshl_b64 s[12:13], s[20:21], 1
	s_add_u32 s12, s8, s12
	s_addc_u32 s13, s9, s13
	s_add_u32 s20, s12, 0x3600000
	s_addc_u32 s68, s13, 0
	s_cmp_lg_u32 s100, 0
	s_cbranch_scc1 .Lmr_a
	s_bitcmp1_b32 s101, 0
	s_cbranch_scc0 .Lmr_a
	s_mov_b32 s100, 1
	s_branch .LBB0_1062
.Lmr_a:
	s_and_b64 vcc, exec, s[56:57]
	s_cbranch_vccnz .LBB0_1062
	v_mbcnt_lo_u32_b32 v0, -1, v0
	s_waitcnt vmcnt(0)
	v_mbcnt_hi_u32_b32 v12, -1, v0
	v_lshl_add_u32 v0, v12, 4, s95
	v_ashrrev_i32_e32 v1, 31, v0
	v_lshrrev_b32_e32 v1, 22, v1
	v_add_u32_e32 v1, v0, v1
	v_ashrrev_i32_e32 v8, 10, v1
	v_mul_i32_i24_e32 v1, 0x400, v8
	v_sub_u32_e32 v1, v0, v1
	v_lshrrev_b32_e32 v2, 4, v1
	v_bitop3_b32 v1, v2, v1, 32 bitop3:0x6c
	v_ashrrev_i32_e32 v3, 31, v1
	v_lshrrev_b32_e32 v3, 26, v3
	v_add_u32_e32 v3, v1, v3
	v_lshlrev_b32_e32 v2, 3, v8
	v_ashrrev_i32_e32 v9, 6, v3
	v_and_b32_e32 v3, 0xc0, v3
	v_and_b32_e32 v2, -16, v2
	v_sub_u32_e32 v1, v1, v3
	v_add_u32_e32 v2, v9, v2
	v_ashrrev_i16_sdwa v1, v213, sext(v1) dst_sel:DWORD dst_unused:UNUSED_PAD src0_sel:DWORD src1_sel:BYTE_0
	v_lshlrev_b32_e32 v4, 5, v8
	v_bfe_i32 v10, v1, 0, 16
	v_lshlrev_b32_e32 v1, 1, v2
	v_lshrrev_b32_e32 v3, 2, v2
	v_and_b32_e32 v5, 3, v9
	s_mov_b32 s12, 0x1fffe0
	v_and_b32_e32 v4, 32, v4
	v_and_b32_e32 v1, 24, v1
	v_and_b32_e32 v3, 4, v3
	v_and_or_b32 v5, v2, s12, v5
	v_or3_b32 v1, v5, v3, v1
	v_add_lshl_u32 v3, v4, v10, 1
	v_add_u32_e32 v0, 0x2000, v0
	v_lshl_add_u32 v172, v1, 11, v3
	v_ashrrev_i32_e32 v1, 31, v0
	v_lshrrev_b32_e32 v1, 22, v1
	v_add_u32_e32 v1, v0, v1
	v_ashrrev_i32_e32 v11, 10, v1
	v_mul_i32_i24_e32 v1, 0x400, v11
	v_sub_u32_e32 v0, v0, v1
	v_lshrrev_b32_e32 v1, 4, v0
	v_bitop3_b32 v0, v1, v0, 32 bitop3:0x6c
	v_lshl_add_u32 v160, v2, 11, v3
	v_ashrrev_i32_e32 v2, 31, v0
	v_lshrrev_b32_e32 v2, 26, v2
	v_add_u32_e32 v2, v0, v2
	v_ashrrev_i32_e32 v13, 6, v2
	v_and_b32_e32 v2, 0xffc0, v2
	v_lshlrev_b32_e32 v1, 3, v11
	v_sub_u32_e32 v0, v0, v2
	v_and_b32_e32 v1, -16, v1
	v_lshrrev_b16_e32 v2, 7, v0
	v_add_u32_e32 v1, v13, v1
	v_and_b32_e32 v2, 1, v2
	v_and_b32_e32 v4, 3, v13
	s_ashr_i32 s61, s60, 31
	s_ashr_i32 s53, s52, 31
	v_add_u16_e32 v0, v0, v2
	v_and_or_b32 v4, v1, s12, v4
	s_lshl_b64 s[12:13], s[60:61], 19
	s_lshl_b64 s[16:17], s[52:53], 19
	v_ashrrev_i16_sdwa v0, v213, sext(v0) dst_sel:DWORD dst_unused:UNUSED_PAD src0_sel:DWORD src1_sel:BYTE_0
	s_add_u32 s62, s20, s16
	v_lshlrev_b32_e32 v3, 5, v11
	v_bfe_i32 v14, v0, 0, 16
	v_lshlrev_b32_e32 v0, 1, v1
	v_lshrrev_b32_e32 v2, 2, v1
	s_addc_u32 s63, s68, s17
	s_add_i32 s69, s95, 0
	v_and_b32_e32 v3, 32, v3
	v_and_b32_e32 v0, 24, v0
	v_and_b32_e32 v2, 4, v2
	s_add_i32 m0, s69, 0x10000
	v_or3_b32 v0, v4, v2, v0
	v_add_lshl_u32 v2, v3, v14, 1
	global_load_lds_dwordx4 v172, s[62:63]
	s_add_i32 m0, s69, 0x12000
	v_lshl_add_u32 v164, v0, 11, v2
	s_add_u32 s16, s62, 0x40000
	global_load_lds_dwordx4 v164, s[62:63]
	s_addc_u32 s17, s63, 0
	s_add_i32 m0, s69, 0x14000
	v_lshl_add_u32 v162, v1, 11, v2
	global_load_lds_dwordx4 v172, s[16:17]
	s_add_i32 m0, s69, 0x16000
	s_add_u32 s64, s14, s12
	s_addc_u32 s65, s15, s13
	s_add_i32 s70, s69, 0x2000
	global_load_lds_dwordx4 v164, s[16:17]
	s_mov_b32 m0, s69
	s_add_u32 s12, s64, 0x40000
	global_load_lds_dwordx4 v160, s[64:65]
	s_mov_b32 m0, s70
	s_addc_u32 s13, s65, 0
	s_add_i32 s71, s69, 0x4000
	global_load_lds_dwordx4 v162, s[64:65]
	s_mov_b32 m0, s71
	s_add_i32 s72, s69, 0x6000
	global_load_lds_dwordx4 v160, s[12:13]
	s_mov_b32 m0, s72
	v_mov_b32_e32 v165, v173
	global_load_lds_dwordx4 v162, s[12:13]
	v_readlane_b32 s12, v243, 60
	v_readlane_b32 s13, v243, 61
	v_mov_b32_e32 v161, v173
	v_mov_b32_e32 v163, v173
	v_cndmask_b32_e64 v15, 0, 1, s[12:13]
	v_lshl_add_u64 v[0:1], s[62:63], 0, v[172:173]
	v_lshl_add_u64 v[2:3], s[62:63], 0, v[164:165]
	v_lshl_add_u64 v[4:5], s[64:65], 0, v[160:161]
	v_lshl_add_u64 v[6:7], s[64:65], 0, v[162:163]
	v_cmp_ne_u32_e64 s[56:57], 1, v15
	s_andn2_b64 vcc, exec, s[12:13]
	s_cbranch_vccnz .LBB0_937
	s_barrier

; #define GAS __attribute__((address_space(1)))
; __device__ __forceinline__ int lane_id() { unsigned z = 0u; asm volatile("" : "+v"(z)); return (int)__builtin_amdgcn_mbcnt_hi(~0u, __builtin_amdgcn_mbcnt_lo(~0u, z)); }
;     __device__ __forceinline__ GAS unsigned char* wsp() const { return (GAS unsigned char*)rd(18); }
; #define PG8_WAIT_V(n) asm volatile("s_waitcnt vmcnt(" #n ")" ::: "memory")
;     const int wid = wave_id, lane = lane_id(), tid = wid * 64 + lane; const int wr = wid >> 2, wc = wid & 3, fr = lane & 15, fq = lane >> 4;
;     const int K = g.K;
;     unsigned voffA[2], voffB[2];
; #pragma unroll
;     for (int i = 0; i < 2; ++i) { int R, C; stage_rc(tid * 16 + i * 8192, R, C); const int Rb = (R & ~31) + perm32(R & 31);
;         voffA[i] = (unsigned)(R * K + C) * 2u; voffB[i] = (unsigned)(Rb * K + C) * 2u; }
;     const size_t kstep = (size_t)(BK * 2);
;     const size_t hstep = (size_t)HALF * K * 2;
;     const size_t tstep = 2 * hstep;
;     const unsigned ldsw = (unsigned)wid * 1024u;
;     const int aoff = lds_byte(wr * 64 + fr, fq * 8), boff = lds_byte(wc * 32 + fr, fq * 8);
;     ...
;     Unit cur, nxt; int ui = 0;
;     if (!S.template next<MODE>(0, cur)) return;
;     Acc acc;
; #pragma unroll
;     for (int a = 0; a < 2; ++a)
; #pragma unroll
;         for (int b = 0; b < 2; ++b)
; #pragma unroll
;             for (int m = 0; m < 4; ++m)
; #pragma unroll
;                 for (int n = 0; n < 2; ++n) acc[a][b][m][n] = (f32x4){0.f, 0.f, 0.f, 0.f};
;     bf16x8 At[4][2], B0[2][2], B1[2][2];
;     const GAS char* cA = (const GAS char*)(g.A + (size_t)cur.seg * g.a_seg) + (size_t)cur.pm * tstep + (MODE ? (size_t)cur.k0 * kstep : 0); const GAS char* cB = (const GAS char*)(g.Bt + (size_t)cur.seg * g.b_seg) + (size_t)cur.pn * tstep + (MODE ? (size_t)cur.k0 * kstep : 0);
;     PG8_STAGE(PG8_SB(0, 0), cB, voffB); PG8_STAGE(PG8_SB(0, 1), cB + hstep, voffB); PG8_STAGE(PG8_SA(0, 0), cA, voffA); PG8_STAGE(PG8_SA(0, 1), cA + hstep, voffA);
;     if (wr == 1) PG8_BAR;
;     PG8_WAIT_V(2); PG8_BAR;
;     PG8_STAGE(PG8_SB(1, 0), cB + kstep, voffB); PG8_STAGE(PG8_SA(1, 0), cA + kstep, voffA); PG8_STAGE(PG8_SB(1, 1), cB + hstep + kstep, voffB);
; __global__ void __launch_bounds__(512, 2) mega_fwd(Params p) {
;     ...
;             { __syncthreads(); pg8::EpiMergeSlab E2{F.wsp()}; pg8::gemm_phase<pg8::EpiMergeSlab, 1>(F.lds, g, S, E2, F.wave); }
.LBB0_1062:
	v_mov_b32_e32 v0, s18
	s_waitcnt vmcnt(0)
	s_barrier
	ds_read_b64 v[0:1], v0
	v_readlane_b32 s12, v242, 46
	v_readlane_b32 s13, v242, 47
	s_andn2_b64 vcc, exec, s[12:13]
	s_waitcnt lgkmcnt(0)
	v_readfirstlane_b32 s9, v1
	v_readfirstlane_b32 s8, v0
	v_mov_b32_e32 v0, v173
	s_cmp_eq_u32 s100, 2
	s_cbranch_scc0 .Lmr_b
	s_mov_b32 s100, 0
	s_branch .LBB0_1070
.Lmr_b:
	s_cbranch_vccnz .LBB0_1070
	v_mbcnt_lo_u32_b32 v0, -1, v0
	v_mbcnt_hi_u32_b32 v135, -1, v0
	v_lshl_add_u32 v0, v135, 4, s95
	v_add_u32_e32 v1, 0x2000, v0
	v_ashrrev_i32_e32 v2, 31, v1
	v_lshrrev_b32_e32 v2, 22, v2
	v_add_u32_e32 v2, v1, v2
	v_ashrrev_i32_e32 v2, 10, v2
	v_mul_i32_i24_e32 v3, 0x400, v2
	v_sub_u32_e32 v1, v1, v3
	v_lshrrev_b32_e32 v3, 4, v1
	v_bitop3_b32 v1, v3, v1, 32 bitop3:0x6c
	v_ashrrev_i32_e32 v3, 31, v1
	v_lshrrev_b32_e32 v3, 26, v3
	v_add_u32_e32 v3, v1, v3
	v_ashrrev_i32_e32 v4, 6, v3
	v_and_b32_e32 v3, 0xffc0, v3
	v_sub_u32_e32 v1, v1, v3
	v_lshlrev_b32_e32 v5, 3, v2
	v_lshrrev_b16_e32 v3, 7, v1
	v_and_b32_e32 v5, -16, v5
	v_and_b32_e32 v3, 1, v3
	v_add_u32_e32 v5, v4, v5
	v_add_u16_e32 v1, v1, v3
	v_and_b32_e32 v4, 3, v4
	s_mov_b32 s12, 0x1fffe0
	v_lshrrev_b32_e32 v6, 2, v5
	v_lshlrev_b32_e32 v7, 1, v5
	v_lshlrev_b32_e32 v2, 5, v2
	v_ashrrev_i16_sdwa v1, v213, sext(v1) dst_sel:DWORD dst_unused:UNUSED_PAD src0_sel:DWORD src1_sel:BYTE_0
	v_and_or_b32 v4, v5, s12, v4
	v_and_b32_e32 v6, 4, v6
	v_and_b32_e32 v7, 24, v7
	v_and_b32_e32 v2, 32, v2
	v_bfe_i32 v1, v1, 0, 16
	v_or3_b32 v4, v4, v6, v7
	v_add_lshl_u32 v1, v2, v1, 1
	v_lshl_add_u32 v128, v4, 11, v1
	v_lshl_add_u32 v130, v5, 11, v1
	v_ashrrev_i32_e32 v1, 31, v0
	v_lshrrev_b32_e32 v1, 22, v1
	v_add_u32_e32 v1, v0, v1
	v_ashrrev_i32_e32 v1, 10, v1
	v_mul_i32_i24_e32 v2, 0x400, v1
	v_sub_u32_e32 v0, v0, v2
	v_lshrrev_b32_e32 v2, 4, v0
	v_bitop3_b32 v0, v2, v0, 32 bitop3:0x6c
	v_ashrrev_i32_e32 v2, 31, v0
	v_lshrrev_b32_e32 v2, 26, v2
	v_add_u32_e32 v2, v0, v2
	v_lshlrev_b32_e32 v4, 3, v1
	v_ashrrev_i32_e32 v3, 6, v2
	v_and_b32_e32 v4, -16, v4
	v_add_u32_e32 v4, v3, v4
	v_and_b32_e32 v3, 3, v3
	v_and_or_b32 v3, v4, s12, v3
	v_readlane_b32 s12, v241, 14
	s_add_u32 s12, s14, s12
	v_readlane_b32 s13, v241, 13
	s_addc_u32 s13, s15, s13
	v_readlane_b32 s16, v241, 3
	v_readlane_b32 s17, v241, 4
	s_add_u32 s15, s12, s16
	s_addc_u32 s24, s13, s17
	v_readlane_b32 s12, v241, 11
	v_readlane_b32 s13, v241, 12
	s_add_u32 s12, s20, s12
	v_and_b32_e32 v2, 0xc0, v2
	s_addc_u32 s13, s68, s13
	v_readlane_b32 s16, v241, 5
	v_sub_u32_e32 v0, v0, v2
	v_readlane_b32 s17, v241, 6
	s_add_u32 s12, s12, s16
	v_lshrrev_b32_e32 v5, 2, v4
	v_lshlrev_b32_e32 v6, 1, v4
	v_lshlrev_b32_e32 v1, 5, v1
	v_ashrrev_i16_sdwa v0, v213, sext(v0) dst_sel:DWORD dst_unused:UNUSED_PAD src0_sel:DWORD src1_sel:BYTE_0
	s_addc_u32 s13, s13, s17
	v_readlane_b32 s26, v241, 0
	v_and_b32_e32 v5, 4, v5
	v_and_b32_e32 v6, 24, v6
	v_and_b32_e32 v1, 32, v1
	v_bfe_i32 v0, v0, 0, 16
	v_readlane_b32 s27, v241, 1
	s_add_u32 s12, s12, s26
	v_or3_b32 v3, v3, v5, v6
	v_add_lshl_u32 v0, v1, v0, 1
	s_addc_u32 s13, s13, s27
	s_add_i32 s14, s95, 0
	v_lshl_add_u32 v172, v3, 11, v0
	s_add_i32 m0, s14, 0x10000
	v_lshl_add_u32 v132, v4, 11, v0
	global_load_lds_dwordx4 v172, s[12:13]
	s_add_i32 m0, s14, 0x12000
	s_add_u32 s16, s12, 0x40000
	global_load_lds_dwordx4 v128, s[12:13]
	s_addc_u32 s17, s13, 0
	s_add_i32 m0, s14, 0x14000
	s_nop 0
	global_load_lds_dwordx4 v172, s[16:17]
	s_add_i32 m0, s14, 0x16000
	s_nop 0
	global_load_lds_dwordx4 v128, s[16:17]
	s_add_u32 s16, s15, s26
	s_addc_u32 s17, s24, s27
	s_add_i32 s15, s14, 0x2000
	s_mov_b32 m0, s14
	s_add_u32 s24, s16, 0x40000
	global_load_lds_dwordx4 v132, s[16:17]
	s_mov_b32 m0, s15
	s_addc_u32 s25, s17, 0
	s_add_i32 s56, s14, 0x4000
	global_load_lds_dwordx4 v130, s[16:17]
	s_mov_b32 m0, s56
	s_add_i32 s57, s14, 0x6000
	global_load_lds_dwordx4 v132, s[24:25]
	s_mov_b32 m0, s57
	v_readlane_b32 s26, v243, 60
	global_load_lds_dwordx4 v130, s[24:25]
	v_readlane_b32 s27, v243, 61
	s_andn2_b64 vcc, exec, s[26:27]
	s_cbranch_vccnz .LBB0_1065
	s_barrier

; #define GAS __attribute__((address_space(1)))
;     __device__ __forceinline__ GAS unsigned char* wsp() const { return (GAS unsigned char*)rd(18); }
; #define SEAM(k) do { if (IN(k) && IN((k) + 1)) xcd_barrier(bar, F.wave); } while (0)
; __global__ void __launch_bounds__(512, 2) mega_fwd(Params p) {
;     ...
;         if (IN(pb + 3)) { pg8::Gemm g{(const GAS bf16*)(F.wsp() + WS_Y), (const GAS bf16*)(F.wsp() + WS_WBR) + (size_t)l * 3 * D * D, (size_t)MTOT * 1024, (size_t)D * D, MTOT / 256, D / 256, 3, D, MERGE_TAIL, WGM_SQ};
;             pg8::Order S; S.init(g, F.G, (int)blockIdx.x);
;             pg8::EpiMerge E{F.wsp()};
;             pg8::gemm_phase(F.lds, g, S, E, F.wave);
;             { __syncthreads(); pg8::EpiMergeSlab E2{F.wsp()}; pg8::gemm_phase<pg8::EpiMergeSlab, 1>(F.lds, g, S, E2, F.wave); }
;             } SEAM(pb + 3);
.LBB0_1070:
	s_cmp_eq_u32 s100, 1
	s_cbranch_scc0 .Lmr_end
	s_mov_b32 s100, 2
	s_branch .Lmr_pre

; __global__ void __launch_bounds__(512, 2) mega_fwd(Params p) {
	.amdhsa_kernel _Z8mega_fwd6Params
		.amdhsa_group_segment_fixed_size 0
		.amdhsa_private_segment_fixed_size 0
		.amdhsa_kernarg_size 416
		.amdhsa_user_sgpr_count 2
		.amdhsa_user_sgpr_dispatch_ptr 0
		.amdhsa_user_sgpr_queue_ptr 0
		.amdhsa_user_sgpr_kernarg_segment_ptr 1
		.amdhsa_user_sgpr_dispatch_id 0
		.amdhsa_user_sgpr_kernarg_preload_length 0
		.amdhsa_user_sgpr_kernarg_preload_offset 0
		.amdhsa_user_sgpr_private_segment_size 0
		.amdhsa_uses_dynamic_stack 0
		.amdhsa_enable_private_segment 0
		.amdhsa_system_sgpr_workgroup_id_x 1
		.amdhsa_system_sgpr_workgroup_id_y 0
		.amdhsa_system_sgpr_workgroup_id_z 0
		.amdhsa_system_sgpr_workgroup_info 0
		.amdhsa_system_vgpr_workitem_id 0
		.amdhsa_next_free_vgpr 252
		.amdhsa_next_free_sgpr 102
		.amdhsa_accum_offset 252
		.amdhsa_reserve_vcc 1
		.amdhsa_float_round_mode_32 0
		.amdhsa_float_round_mode_16_64 0
		.amdhsa_float_denorm_mode_32 3
		.amdhsa_float_denorm_mode_16_64 3
		.amdhsa_dx10_clamp 1
		.amdhsa_ieee_mode 1
		.amdhsa_fp16_overflow 0
		.amdhsa_tg_split 0
		.amdhsa_exception_fp_ieee_invalid_op 0
		.amdhsa_exception_fp_denorm_src 0
		.amdhsa_exception_fp_ieee_div_zero 0
		.amdhsa_exception_fp_ieee_overflow 0
		.amdhsa_exception_fp_ieee_underflow 0
		.amdhsa_exception_fp_ieee_inexact 0
		.amdhsa_exception_int_div_zero 0
	.end_amdhsa_kernel

; __global__ void __launch_bounds__(512, 2) mega_fwd(Params p) {
amdhsa.kernels:
  - .agpr_count:     0
    .args:
      - .offset:         0
        .size:           160
        .value_kind:     by_value
      - .offset:         160
        .size:           4
        .value_kind:     hidden_block_count_x
      - .offset:         164
        .size:           4
        .value_kind:     hidden_block_count_y
      - .offset:         168
        .size:           4
        .value_kind:     hidden_block_count_z
      - .offset:         172
        .size:           2
        .value_kind:     hidden_group_size_x
      - .offset:         174
        .size:           2
        .value_kind:     hidden_group_size_y
      - .offset:         176
        .size:           2
        .value_kind:     hidden_group_size_z
      - .offset:         178
        .size:           2
        .value_kind:     hidden_remainder_x
      - .offset:         180
        .size:           2
        .value_kind:     hidden_remainder_y
      - .offset:         182
        .size:           2
        .value_kind:     hidden_remainder_z
      - .offset:         200
        .size:           8
        .value_kind:     hidden_global_offset_x
      - .offset:         208
        .size:           8
        .value_kind:     hidden_global_offset_y
      - .offset:         216
        .size:           8
        .value_kind:     hidden_global_offset_z
      - .offset:         224
        .size:           2
        .value_kind:     hidden_grid_dims
      - .offset:         280
        .size:           4
        .value_kind:     hidden_dynamic_lds_size
    .group_segment_fixed_size: 0
    .kernarg_segment_align: 8
    .kernarg_segment_size: 416
    .language:       OpenCL C
    .language_version:
      - 2
      - 0
    .max_flat_workgroup_size: 512
    .name:           _Z8mega_fwd6Params
    .private_segment_fixed_size: 0
    .sgpr_count:     108
    .sgpr_spill_count: 252
    .symbol:         _Z8mega_fwd6Params.kd
    .uniform_work_group_size: 1
    .uses_dynamic_stack: false
    .vgpr_count:     252
    .vgpr_spill_count: 0
    .wavefront_size: 64
